# v35 + attention loop PV n=0 half software-pipelined (P fragments prefetched, counted lgkmcnt)
# speedup vs baseline: 1.0410x; 1.0006x over previous
; __device__ __forceinline__ void phase_attention(const Params& p, int half, unsigned char* lds) {
;     ...
;             const int dp = wv & 3, qh = wv >> 2;
;             f32x4 o[2][2] = {{{0.f, 0.f, 0.f, 0.f}, {0.f, 0.f, 0.f, 0.f}}, {{0.f, 0.f, 0.f, 0.f}, {0.f, 0.f, 0.f, 0.f}}};
;             {
;                 typedef unsigned short u16x4 __attribute__((ext_vector_type(4)));
;                 const int s1 = (sl0 + 1 >= 3) ? sl0 - 2 : sl0 + 1, s2 = (sl0 + 2 >= 3) ? sl0 - 1 : sl0 + 2;
;                 const unsigned lane_off = (unsigned)(((8 * fq + ((lane & 15) >> 2)) * QS + 32 * dp + 8 * (lane & 3)) * 2);
;                 const unsigned vs_base = (unsigned)(unsigned long long)(const __attribute__((address_space(3))) void*)Vs;
;                 const unsigned a0 = vs_base + sl0 * (64 * QS * 2) + lane_off, a1 = vs_base + s1 * (64 * QS * 2) + lane_off, a2 = vs_base + s2 * (64 * QS * 2) + lane_off;
; #pragma unroll
;                 for (int n = 0; n < 2; ++n) {
;                     u16x4 vt[12];
;                     const unsigned b0 = a0 + 8 * n, b1 = a1 + 8 * n, b2 = a2 + 8 * n;
;                     asm volatile(
;                         "ds_read_b64_tr_b16 %0, %12\n\tds_read_b64_tr_b16 %1, %12 offset:1088\n\t"
;                         "ds_read_b64_tr_b16 %2, %12 offset:8704\n\tds_read_b64_tr_b16 %3, %12 offset:9792\n\t"
;                         "ds_read_b64_tr_b16 %4, %13\n\tds_read_b64_tr_b16 %5, %13 offset:1088\n\t"
;                         "ds_read_b64_tr_b16 %6, %13 offset:8704\n\tds_read_b64_tr_b16 %7, %13 offset:9792\n\t"
;                         "ds_read_b64_tr_b16 %8, %14\n\tds_read_b64_tr_b16 %9, %14 offset:1088\n\t"
;                         "ds_read_b64_tr_b16 %10, %14 offset:8704\n\tds_read_b64_tr_b16 %11, %14 offset:9792\n\t"
;                         "s_waitcnt lgkmcnt(0)"
;                         : "=&v"(vt[0]), "=&v"(vt[1]), "=&v"(vt[2]), "=&v"(vt[3]), "=&v"(vt[4]), "=&v"(vt[5]),
;                           "=&v"(vt[6]), "=&v"(vt[7]), "=&v"(vt[8]), "=&v"(vt[9]), "=&v"(vt[10]), "=&v"(vt[11])
;                         : "v"(b0), "v"(b1), "v"(b2) : "memory");
; #pragma unroll
;                     for (int kk = 0; kk < 6; ++kk) {
;                         bf16x8 vfr;
; #pragma unroll
;                         for (int e = 0; e < 4; ++e) { vfr[e] = (short)vt[2 * kk][e]; vfr[4 + e] = (short)vt[2 * kk + 1][e]; }
; #pragma unroll
.LBB0_185:
	s_or_b64 exec, exec, s[16:17]
	s_cmp_gt_i32 s2, 1
	s_cselect_b32 s3, -2, 1
	s_add_i32 s3, s3, s2
	s_cmp_gt_i32 s2, 0
	s_cselect_b32 s16, -1, 2
	s_add_i32 s16, s16, s2
	s_mulk_i32 s2, 0x4400
	s_mulk_i32 s3, 0x4400
	s_mulk_i32 s16, 0x4400
	s_waitcnt lgkmcnt(0)
	s_barrier
	v_add_u32_e32 v64, s2, v141
	v_add_u32_e32 v65, s3, v141
	v_add_u32_e32 v105, s16, v141
	ds_read_b64_tr_b16 v[184:185], v64
	ds_read_b64_tr_b16 v[186:187], v64 offset:1088
	ds_read_b64_tr_b16 v[160:161], v64 offset:8704
	ds_read_b64_tr_b16 v[162:163], v64 offset:9792
	ds_read_b64_tr_b16 v[72:73], v65
	ds_read_b64_tr_b16 v[74:75], v65 offset:1088
	ds_read_b64_tr_b16 v[68:69], v65 offset:8704
	ds_read_b64_tr_b16 v[70:71], v65 offset:9792
	ds_read_b64_tr_b16 v[60:61], v105
	ds_read_b64_tr_b16 v[62:63], v105 offset:1088
	ds_read_b64_tr_b16 v[56:57], v105 offset:8704
	ds_read_b64_tr_b16 v[58:59], v105 offset:9792
	ds_read_b128 v[208:211], v182
	ds_read_b128 v[212:215], v182 offset:6400
	ds_read_b128 v[216:219], v182 offset:64
	s_waitcnt lgkmcnt(1)
	v_mfma_f32_16x16x32_bf16 v[240:243], v[184:187], v[208:211], 0
	v_mfma_f32_16x16x32_bf16 v[244:247], v[184:187], v[212:215], 0
	v_or_b32_e32 v64, 8, v64
	v_or_b32_e32 v65, 8, v65
	ds_read_b128 v[220:223], v182 offset:6464
	ds_read_b128 v[224:227], v182 offset:128
	ds_read_b128 v[228:231], v182 offset:6528
	s_waitcnt lgkmcnt(2)
	v_mfma_f32_16x16x32_bf16 v[240:243], v[160:163], v[216:219], v[240:243]
	v_mfma_f32_16x16x32_bf16 v[244:247], v[160:163], v[220:223], v[244:247]
	ds_read_b128 v[208:211], v182 offset:192
	ds_read_b128 v[212:215], v182 offset:6592
	s_waitcnt lgkmcnt(2)
	v_mfma_f32_16x16x32_bf16 v[240:243], v[72:75], v[224:227], v[240:243]
	v_mfma_f32_16x16x32_bf16 v[244:247], v[72:75], v[228:231], v[244:247]
	ds_read_b128 v[216:219], v182 offset:256
	ds_read_b128 v[220:223], v182 offset:6656
	s_waitcnt lgkmcnt(2)
	v_mfma_f32_16x16x32_bf16 v[240:243], v[68:71], v[208:211], v[240:243]
	v_mfma_f32_16x16x32_bf16 v[244:247], v[68:71], v[212:215], v[244:247]
	ds_read_b128 v[224:227], v182 offset:320
	ds_read_b128 v[228:231], v182 offset:6720
	s_waitcnt lgkmcnt(2)
	v_mfma_f32_16x16x32_bf16 v[240:243], v[60:63], v[216:219], v[240:243]
	v_mfma_f32_16x16x32_bf16 v[244:247], v[60:63], v[220:223], v[244:247]
	s_waitcnt lgkmcnt(0)
	v_mfma_f32_16x16x32_bf16 v[70:73], v[56:59], v[224:227], v[240:243]
	v_mfma_f32_16x16x32_bf16 v[56:59], v[56:59], v[228:231], v[244:247]
	v_or_b32_e32 v68, 8, v105
	ds_read_b64_tr_b16 v[196:197], v64
	ds_read_b64_tr_b16 v[198:199], v64 offset:1088
	ds_read_b64_tr_b16 v[192:193], v64 offset:8704
	ds_read_b64_tr_b16 v[194:195], v64 offset:9792
	ds_read_b64_tr_b16 v[188:189], v65
	ds_read_b64_tr_b16 v[190:191], v65 offset:1088
	ds_read_b64_tr_b16 v[184:185], v65 offset:8704
	ds_read_b64_tr_b16 v[186:187], v65 offset:9792
	ds_read_b64_tr_b16 v[160:161], v68
	ds_read_b64_tr_b16 v[162:163], v68 offset:1088
	ds_read_b64_tr_b16 v[60:61], v68 offset:8704
	ds_read_b64_tr_b16 v[62:63], v68 offset:9792
	s_waitcnt lgkmcnt(0)
	ds_read_b128 v[200:203], v182
	ds_read_b128 v[204:207], v182 offset:6400
	s_waitcnt lgkmcnt(1)
	v_mfma_f32_16x16x32_bf16 v[200:203], v[196:199], v[200:203], 0
	ds_read2st64_b32 v[64:65], v149 offset0:2 offset1:3
	v_add_u32_e32 v68, s66, v103
	s_waitcnt lgkmcnt(0)
	v_add_f32_e32 v69, v64, v65
	v_mfma_f32_16x16x32_bf16 v[196:199], v[196:199], v[204:207], 0
	ds_read_b128 v[204:207], v182 offset:64
	v_rcp_f32_e32 v74, v69
	v_lshlrev_b32_e32 v64, s59, v68
	s_waitcnt lgkmcnt(0)
	v_mfma_f32_16x16x32_bf16 v[200:203], v[192:195], v[204:207], v[200:203]
	ds_read_b128 v[204:207], v182 offset:6464
	v_mul_f32_e32 v70, v70, v74
	v_mul_f32_e32 v71, v71, v74
	s_waitcnt lgkmcnt(0)
	v_mfma_f32_16x16x32_bf16 v[192:195], v[192:195], v[204:207], v[196:199]
	v_add_u32_e32 v64, s63, v64
	s_nop 1
	ds_read_b128 v[196:199], v182 offset:128
	v_cvt_pk_bf16_f32 v70, v70, v71
	s_waitcnt lgkmcnt(0)
	v_mfma_f32_16x16x32_bf16 v[196:199], v[188:191], v[196:199], v[200:203]
	s_nop 2
	ds_read_b128 v[200:203], v182 offset:6528
	v_mul_f32_e32 v71, v72, v74
	v_mul_f32_e32 v72, v73, v74
	s_waitcnt lgkmcnt(0)
	v_mfma_f32_16x16x32_bf16 v[188:191], v[188:191], v[200:203], v[192:195]
	v_ashrrev_i32_e32 v65, 31, v64
	s_nop 1
	ds_read_b128 v[192:195], v182 offset:192
	v_cvt_pk_bf16_f32 v71, v71, v72
	s_waitcnt lgkmcnt(0)
	v_mfma_f32_16x16x32_bf16 v[192:195], v[184:187], v[192:195], v[196:199]
	s_nop 2
	ds_read_b128 v[196:199], v182 offset:6592
	v_lshl_add_u64 v[64:65], s[98:99], 0, v[64:65]
	s_waitcnt lgkmcnt(0)
	v_mfma_f32_16x16x32_bf16 v[184:187], v[184:187], v[196:199], v[188:191]
	s_nop 2
	ds_read_b128 v[188:191], v182 offset:256
	s_waitcnt lgkmcnt(0)
	v_mfma_f32_16x16x32_bf16 v[188:191], v[160:163], v[188:191], v[192:195]
	s_nop 2
	ds_read_b128 v[192:195], v182 offset:6656
	s_waitcnt lgkmcnt(0)
	v_mfma_f32_16x16x32_bf16 v[160:163], v[160:163], v[192:195], v[184:187]
	s_nop 2
	ds_read_b128 v[184:187], v182 offset:320
	s_waitcnt lgkmcnt(0)
	v_mfma_f32_16x16x32_bf16 v[184:187], v[60:63], v[184:187], v[188:191]
	s_nop 2
	ds_read_b128 v[188:191], v182 offset:6720
	s_waitcnt lgkmcnt(0)
	v_mfma_f32_16x16x32_bf16 v[60:63], v[60:63], v[188:191], v[160:163]
	s_nop 1
	v_mul_f32_e32 v72, v184, v74
	v_mul_f32_e32 v73, v185, v74
	v_cvt_pk_bf16_f32 v72, v72, v73
	v_mul_f32_e32 v73, v186, v74
	v_mul_f32_e32 v74, v187, v74
	v_cvt_pk_bf16_f32 v73, v73, v74
	v_lshlrev_b64 v[74:75], 12, v[64:65]
	v_lshl_add_u64 v[74:75], v[100:101], 0, v[74:75]
	global_store_dwordx4 v[74:75], v[70:73], off
	s_and_saveexec_b64 s[30:31], s[94:95]
	s_cbranch_execz .LBB0_187
	ds_read2st64_b32 v[70:71], v149 offset1:1
	v_cmp_gt_f32_e32 vcc, s82, v69
	v_lshlrev_b64 v[64:65], 6, v[64:65]
	v_lshl_add_u64 v[64:65], s[24:25], 0, v[64:65]
	v_cndmask_b32_e64 v72, 0, 32, vcc
	v_ldexp_f32 v69, v69, v72
	v_log_f32_e32 v69, v69
	s_waitcnt lgkmcnt(0)
	v_max_f32_e32 v71, v71, v71
	v_max_f32_e32 v70, v70, v70
	v_max_f32_e32 v70, v70, v71
	v_cndmask_b32_e32 v71, 0, v167, vcc
	v_sub_f32_e32 v69, v69, v71
	v_add_f32_e32 v69, v69, v70
	v_mul_f32_e32 v69, 0x3f317218, v69
	global_store_dword v[64:65], v69, off
